# v94 stack + dead address computations removed from the conv tile-start block (left over after the loads were batched)
# baseline (speedup 1.0000x reference)
; #define GLU2(uu) ((f32x2){bflo(uu), bfhi(uu)})
; __global__ void __launch_bounds__(NWAVES * 64, 2) mk_fwd(Args args) {
;     ...
;                 const int R0 = tile * 64, tl0 = R0 % SEQ;
;                 const bf16* zb = Z + (size_t)(R0 + 32 * th) * ZP + 2 * cp;
;                 f32x2 win[38]; unsigned ru[8];
; #pragma unroll
;                 for (int i = 0; i < 38; ++i) win[i] = (f32x2){0.f, 0.f};
;                 if (tl0 + 32 * th > 0) {
; #pragma unroll
;                     for (int i = 0; i < 30; ++i) { const bf16* zr = zb + (long)(i - 30) * ZP; const unsigned uu = *(const unsigned*)zr; win[8 + i] = GLU2(uu); } }
; #pragma unroll
;                 for (int i = 0; i < 8; ++i) { const bf16* zr = zb + (long)i * ZP; ru[i] = *(const unsigned*)zr; }
.LBB0_355:
	s_bfe_i32 s2, s6, 0x10019
	s_lshl_b32 s4, s6, 6
	s_lshr_b32 s2, s2, 21
	s_add_i32 s2, s4, s2
	s_and_b32 s2, s2, 0xfffff800
	v_add_u32_e32 v76, s4, v166
	s_sub_i32 s5, s4, s2
	v_mov_b32_e32 v81, v80
	v_mad_i64_i32 v[60:61], s[2:3], v76, s10, v[146:147]
	v_cmp_gt_i32_e32 vcc, s5, v167
	v_mov_b64_e32 v[64:65], v[80:81]
	v_mov_b64_e32 v[62:63], v[80:81]
	v_mov_b64_e32 v[56:57], v[80:81]
	v_mov_b64_e32 v[54:55], v[80:81]
	v_mov_b64_e32 v[52:53], v[80:81]
	v_mov_b64_e32 v[50:51], v[80:81]
	v_mov_b64_e32 v[38:39], v[80:81]
	v_mov_b64_e32 v[36:37], v[80:81]
	v_mov_b64_e32 v[34:35], v[80:81]
	v_mov_b64_e32 v[32:33], v[80:81]
	v_mov_b64_e32 v[30:31], v[80:81]
	v_mov_b64_e32 v[28:29], v[80:81]
	v_mov_b64_e32 v[26:27], v[80:81]
	v_mov_b64_e32 v[24:25], v[80:81]
	v_mov_b64_e32 v[22:23], v[80:81]
	v_mov_b64_e32 v[20:21], v[80:81]
	v_mov_b64_e32 v[18:19], v[80:81]
	v_mov_b64_e32 v[16:17], v[80:81]
	v_mov_b64_e32 v[46:47], v[80:81]
	v_mov_b64_e32 v[58:59], v[80:81]
	v_mov_b64_e32 v[70:71], v[80:81]
	v_mov_b64_e32 v[72:73], v[80:81]
	v_mov_b64_e32 v[74:75], v[80:81]
	v_mov_b64_e32 v[78:79], v[80:81]
	v_mov_b32_e32 v66, 0
	v_mov_b32_e32 v67, 0
	v_mov_b32_e32 v68, 0
	v_mov_b32_e32 v69, 0
	v_mov_b32_e32 v40, 0
	v_mov_b32_e32 v41, 0
	v_mov_b32_e32 v42, 0
	v_mov_b32_e32 v43, 0
	v_mov_b32_e32 v44, 0
	v_mov_b32_e32 v45, 0
	v_mov_b32_e32 v48, 0
	v_mov_b32_e32 v49, 0
	s_mov_b32 s92, 0x1400
	s_mov_b32 s93, 0
	s_mov_b32 s94, 0xfffda800
	s_mov_b32 s95, -1
	v_mov_b64_e32 v[242:243], v[60:61]
	global_load_dword v232, v[242:243], off
	v_lshl_add_u64 v[242:243], v[242:243], 0, s[92:93]
	global_load_dword v233, v[242:243], off
	v_lshl_add_u64 v[242:243], v[242:243], 0, s[92:93]
	global_load_dword v234, v[242:243], off
	v_lshl_add_u64 v[242:243], v[242:243], 0, s[92:93]
	global_load_dword v235, v[242:243], off
	v_lshl_add_u64 v[242:243], v[242:243], 0, s[92:93]
	global_load_dword v236, v[242:243], off
	v_lshl_add_u64 v[242:243], v[242:243], 0, s[92:93]
	global_load_dword v237, v[242:243], off
	v_lshl_add_u64 v[242:243], v[242:243], 0, s[92:93]
	global_load_dword v238, v[242:243], off
	v_lshl_add_u64 v[242:243], v[242:243], 0, s[92:93]
	global_load_dword v239, v[242:243], off
	s_and_saveexec_b64 s[2:3], vcc
	s_cbranch_execz .LBB0_357
; #define GLU2(uu) ((f32x2){bflo(uu), bfhi(uu)})
; __global__ void __launch_bounds__(NWAVES * 64, 2) mk_fwd(Args args) {
;     ...
;                 if (tl0 + 32 * th > 0) {
; #pragma unroll
;                     for (int i = 0; i < 30; ++i) { const bf16* zr = zb + (long)(i - 30) * ZP; const unsigned uu = *(const unsigned*)zr; win[8 + i] = GLU2(uu); } }
;     ...
;                     for (int i = 0; i < 30; ++i) win[i] = win[i + 8];
; #pragma unroll
;                     for (int i = 0; i < 8; ++i) win[30 + i] = GLU2(ru[i]);
	v_lshl_add_u64 v[240:241], v[60:61], 0, s[94:95]
	global_load_dword v201, v[240:241], off
	v_lshl_add_u64 v[240:241], v[240:241], 0, s[92:93]
	global_load_dword v202, v[240:241], off
	v_lshl_add_u64 v[240:241], v[240:241], 0, s[92:93]
	global_load_dword v203, v[240:241], off
	v_lshl_add_u64 v[240:241], v[240:241], 0, s[92:93]
	global_load_dword v204, v[240:241], off
	v_lshl_add_u64 v[240:241], v[240:241], 0, s[92:93]
	global_load_dword v205, v[240:241], off
	v_lshl_add_u64 v[240:241], v[240:241], 0, s[92:93]
	global_load_dword v206, v[240:241], off
	v_lshl_add_u64 v[240:241], v[240:241], 0, s[92:93]
	global_load_dword v207, v[240:241], off
	v_lshl_add_u64 v[240:241], v[240:241], 0, s[92:93]
	global_load_dword v208, v[240:241], off
	v_lshl_add_u64 v[240:241], v[240:241], 0, s[92:93]
	global_load_dword v209, v[240:241], off
	v_lshl_add_u64 v[240:241], v[240:241], 0, s[92:93]
	global_load_dword v210, v[240:241], off
	v_lshl_add_u64 v[240:241], v[240:241], 0, s[92:93]
	global_load_dword v211, v[240:241], off
	v_lshl_add_u64 v[240:241], v[240:241], 0, s[92:93]
	global_load_dword v212, v[240:241], off
	v_lshl_add_u64 v[240:241], v[240:241], 0, s[92:93]
	global_load_dword v213, v[240:241], off
	v_lshl_add_u64 v[240:241], v[240:241], 0, s[92:93]
	global_load_dword v214, v[240:241], off
	v_lshl_add_u64 v[240:241], v[240:241], 0, s[92:93]
	global_load_dword v215, v[240:241], off
	v_lshl_add_u64 v[240:241], v[240:241], 0, s[92:93]
	global_load_dword v216, v[240:241], off
	v_lshl_add_u64 v[240:241], v[240:241], 0, s[92:93]
	global_load_dword v217, v[240:241], off
	v_lshl_add_u64 v[240:241], v[240:241], 0, s[92:93]
	global_load_dword v218, v[240:241], off
	v_lshl_add_u64 v[240:241], v[240:241], 0, s[92:93]
	global_load_dword v219, v[240:241], off
	v_lshl_add_u64 v[240:241], v[240:241], 0, s[92:93]
	global_load_dword v221, v[240:241], off
	v_lshl_add_u64 v[240:241], v[240:241], 0, s[92:93]
	global_load_dword v222, v[240:241], off
	v_lshl_add_u64 v[240:241], v[240:241], 0, s[92:93]
	global_load_dword v223, v[240:241], off
	v_lshl_add_u64 v[240:241], v[240:241], 0, s[92:93]
	global_load_dword v224, v[240:241], off
	v_lshl_add_u64 v[240:241], v[240:241], 0, s[92:93]
	global_load_dword v225, v[240:241], off
	v_lshl_add_u64 v[240:241], v[240:241], 0, s[92:93]
	global_load_dword v226, v[240:241], off
	v_lshl_add_u64 v[240:241], v[240:241], 0, s[92:93]
	global_load_dword v227, v[240:241], off
	v_lshl_add_u64 v[240:241], v[240:241], 0, s[92:93]
	global_load_dword v228, v[240:241], off
	v_lshl_add_u64 v[240:241], v[240:241], 0, s[92:93]
	global_load_dword v229, v[240:241], off
	v_lshl_add_u64 v[240:241], v[240:241], 0, s[92:93]
	global_load_dword v230, v[240:241], off
	v_lshl_add_u64 v[240:241], v[240:241], 0, s[92:93]
	global_load_dword v231, v[240:241], off
	s_waitcnt vmcnt(0)
	v_mov_b32_e32 v32, v201
	v_mov_b32_e32 v33, v202
	v_mov_b32_e32 v34, v203
	v_mov_b32_e32 v35, v204
	v_mov_b32_e32 v36, v205
	v_mov_b32_e32 v37, v206
	v_mov_b32_e32 v38, v207
	v_mov_b32_e32 v39, v208
	s_waitcnt vmcnt(0) lgkmcnt(0)
	v_lshlrev_b32_e32 v78, 16, v32
	v_and_b32_e32 v79, 0xffff0000, v32
	s_nop 0
	v_lshlrev_b32_e32 v74, 16, v33
	s_nop 0
	v_and_b32_e32 v75, 0xffff0000, v33
	s_nop 0
	v_lshlrev_b32_e32 v72, 16, v34
	s_nop 0
	v_and_b32_e32 v73, 0xffff0000, v34
	s_nop 0
	v_lshlrev_b32_e32 v70, 16, v35
	s_nop 0
	v_and_b32_e32 v71, 0xffff0000, v35
	s_nop 0
	v_mov_b32_e32 v40, v209
	v_mov_b32_e32 v41, v210
	v_mov_b32_e32 v42, v211
	v_mov_b32_e32 v43, v212
	v_mov_b32_e32 v50, v213
	v_mov_b32_e32 v51, v214
	v_mov_b32_e32 v52, v215
	v_mov_b32_e32 v53, v216
	v_lshlrev_b32_e32 v58, 16, v36
	s_nop 0
	v_and_b32_e32 v59, 0xffff0000, v36
	s_nop 0
	v_lshlrev_b32_e32 v46, 16, v37
	s_nop 0
	v_and_b32_e32 v47, 0xffff0000, v37
	s_nop 0
	v_lshlrev_b32_e32 v48, 16, v38
	s_nop 0
	v_and_b32_e32 v49, 0xffff0000, v38
	s_nop 0
	v_lshlrev_b32_e32 v44, 16, v39
	s_nop 0
	v_and_b32_e32 v45, 0xffff0000, v39
	s_nop 0
	v_mov_b32_e32 v54, v217
	v_mov_b32_e32 v55, v218
	v_mov_b32_e32 v56, v219
	v_mov_b32_e32 v57, v221
	v_mov_b32_e32 v62, v222
	v_mov_b32_e32 v63, v223
	v_mov_b32_e32 v64, v224
	v_mov_b32_e32 v65, v225
	s_waitcnt vmcnt(0) lgkmcnt(0)
	v_lshlrev_b32_e32 v26, 16, v51
	v_and_b32_e32 v27, 0xffff0000, v51
	s_nop 0
	v_lshlrev_b32_e32 v28, 16, v54
	s_nop 0
	v_and_b32_e32 v29, 0xffff0000, v54
	s_nop 0
	v_lshlrev_b32_e32 v30, 16, v55
	s_nop 0
	v_mov_b32_e32 v77, v226
	v_mov_b32_e32 v81, v227
	v_mov_b32_e32 v152, v228
	v_mov_b32_e32 v153, v229
	v_mov_b32_e32 v154, v230
	v_add_co_u32_e32 v16, vcc, 0xffffec00, v60
	v_lshlrev_b32_e32 v18, 16, v41
	s_nop 0
	v_addc_co_u32_e32 v17, vcc, -1, v61, vcc
	v_mov_b32_e32 v155, v231
	v_lshlrev_b32_e32 v16, 16, v40
	v_and_b32_e32 v17, 0xffff0000, v40
	v_and_b32_e32 v19, 0xffff0000, v41
	v_lshlrev_b32_e32 v20, 16, v42
	v_and_b32_e32 v21, 0xffff0000, v42
	v_lshlrev_b32_e32 v22, 16, v43
	v_and_b32_e32 v23, 0xffff0000, v43
	v_lshlrev_b32_e32 v24, 16, v50
	v_and_b32_e32 v25, 0xffff0000, v50
	v_lshlrev_b32_e32 v42, 16, v52
	v_and_b32_e32 v43, 0xffff0000, v52
	v_lshlrev_b32_e32 v40, 16, v53
	v_and_b32_e32 v41, 0xffff0000, v53
	v_and_b32_e32 v31, 0xffff0000, v55
	v_lshlrev_b32_e32 v32, 16, v56
	v_and_b32_e32 v33, 0xffff0000, v56
	v_lshlrev_b32_e32 v34, 16, v57
	v_and_b32_e32 v35, 0xffff0000, v57
	v_lshlrev_b32_e32 v36, 16, v62
	v_and_b32_e32 v37, 0xffff0000, v62
	v_lshlrev_b32_e32 v38, 16, v63
	v_and_b32_e32 v39, 0xffff0000, v63
	v_lshlrev_b32_e32 v68, 16, v64
	v_and_b32_e32 v69, 0xffff0000, v64
	v_lshlrev_b32_e32 v66, 16, v65
	v_and_b32_e32 v67, 0xffff0000, v65
	s_waitcnt vmcnt(0) lgkmcnt(0)
	v_lshlrev_b32_e32 v50, 16, v77
	v_and_b32_e32 v51, 0xffff0000, v77
	v_lshlrev_b32_e32 v52, 16, v81
	v_and_b32_e32 v53, 0xffff0000, v81
	v_lshlrev_b32_e32 v54, 16, v152
	v_and_b32_e32 v55, 0xffff0000, v152
	v_lshlrev_b32_e32 v56, 16, v153
	v_and_b32_e32 v57, 0xffff0000, v153
	v_lshlrev_b32_e32 v62, 16, v154
	v_and_b32_e32 v63, 0xffff0000, v154
	v_lshlrev_b32_e32 v64, 16, v155
	v_and_b32_e32 v65, 0xffff0000, v155
